# nt hint on the norm0 x-row prefetch loads (x is read once in this phase), on top of the batched parameter loads
# speedup vs baseline: 1.0149x; 1.0149x over previous
.LBB0_663:
	v_add_u32_e32 v74, s6, v28
	v_min_i32_e32 v56, 0x8000, v28
	v_cmp_gt_i32_e32 vcc, s3, v74
	s_waitcnt vmcnt(0)
	v_pk_mul_f32 v[40:41], v[2:3], v[2:3]
	v_pk_mul_f32 v[42:43], v[6:7], v[6:7]
	v_pk_mul_f32 v[44:45], v[0:1], v[0:1]
	v_pk_mul_f32 v[46:47], v[4:5], v[4:5]
	v_pk_mul_f32 v[48:49], v[14:15], v[14:15]
	v_pk_mul_f32 v[50:51], v[10:11], v[10:11]
	v_pk_mul_f32 v[52:53], v[12:13], v[12:13]
	v_pk_mul_f32 v[54:55], v[8:9], v[8:9]
	v_cndmask_b32_e32 v28, v28, v74, vcc
	v_ashrrev_i32_e32 v60, 12, v56
	v_mov_b32_e32 v56, v52
	v_mov_b32_e32 v57, v54
	v_mov_b32_e32 v54, v53
	v_mov_b32_e32 v52, v48
	v_mov_b32_e32 v53, v50
	v_mov_b32_e32 v50, v49
	v_mov_b32_e32 v48, v44
	v_mov_b32_e32 v49, v46
	v_mov_b32_e32 v46, v45
	v_mov_b32_e32 v44, v40
	v_mov_b32_e32 v45, v42
	v_mov_b32_e32 v42, v41
	v_add_u32_e32 v41, 0xffff8000, v28
	v_mul_i32_i24_e32 v40, 0xc00, v60
	v_cmp_gt_i32_e32 vcc, s14, v28
	v_pk_add_f32 v[46:47], v[48:49], v[46:47]
	global_load_dwordx4 v[36:39], v[18:19], off
	global_load_dwordx4 v[140:143], v[18:19], off offset:1024
	global_load_dwordx4 v[144:147], v[18:19], off offset:2048
	global_load_dwordx4 v[148:151], v[18:19], off offset:3072
	v_cndmask_b32_e32 v48, v41, v28, vcc
	v_ashrrev_i32_e32 v41, 31, v40
	v_lshl_add_u64 v[40:41], v[40:41], 2, s[4:5]
	v_pk_add_f32 v[44:45], v[44:45], v[46:47]
	v_lshl_add_u64 v[66:67], v[40:41], 0, s[12:13]
	v_pk_add_f32 v[64:65], v[42:43], v[44:45]
	v_lshl_add_u64 v[68:69], v[40:41], 0, v[16:17]
	v_lshl_add_u64 v[44:45], v[66:67], 0, v[16:17]
	global_load_dwordx4 v[40:43], v[68:69], off
	global_load_dwordx4 v[152:155], v[68:69], off offset:1024
	global_load_dwordx4 v[156:159], v[68:69], off offset:2048
	global_load_dwordx4 v[160:163], v[68:69], off offset:3072
	s_nop 0
	global_load_dwordx4 v[164:167], v[44:45], off offset:1024
	global_load_dwordx4 v[168:171], v[44:45], off offset:2048
	global_load_dwordx4 v[172:175], v[44:45], off offset:3072
	global_load_dwordx4 v[44:47], v[44:45], off
	v_pk_add_f32 v[54:55], v[56:57], v[54:55]
	v_mov_b32_e32 v25, s57
	v_pk_add_f32 v[52:53], v[52:53], v[54:55]
	v_mov_b32_e32 v27, s53
	v_pk_add_f32 v[50:51], v[50:51], v[52:53]
	v_cndmask_b32_e32 v57, v25, v27, vcc
	v_add_f32_e32 v25, v50, v51
	v_mov_b32_e32 v23, v17
	v_add_f32_e32 v25, v65, v25
	v_lshl_add_u64 v[72:73], v[66:67], 0, v[22:23]
	v_add_f32_e32 v23, v64, v25
	ds_bpermute_b32 v25, v30, v23
	v_mov_b32_e32 v58, s56
	v_mov_b32_e32 v59, s52
	v_ashrrev_i32_e32 v61, 31, v28
	v_cndmask_b32_e32 v49, 0, v61, vcc
	s_waitcnt lgkmcnt(0)
	v_add_f32_e32 v23, v23, v25
	ds_bpermute_b32 v25, v31, v23
	v_cndmask_b32_e32 v56, v58, v59, vcc
	v_lshlrev_b64 v[48:49], 12, v[48:49]
	v_lshl_add_u64 v[48:49], v[56:57], 0, v[48:49]
	v_lshl_add_u64 v[70:71], v[48:49], 0, v[16:17]
	s_waitcnt lgkmcnt(0)
	v_add_f32_e32 v23, v23, v25
	ds_bpermute_b32 v25, v32, v23
	global_load_dwordx4 v[48:51], v[70:71], off nt
	global_load_dwordx4 v[52:55], v[70:71], off offset:1024 nt
	global_load_dwordx4 v[56:59], v[70:71], off offset:2048 nt
	global_load_dwordx4 v[60:63], v[70:71], off offset:3072 nt
	v_mov_b32_e32 v27, v17
	v_mov_b32_e32 v28, v74
	s_waitcnt lgkmcnt(0)
	v_add_f32_e32 v23, v23, v25
	ds_bpermute_b32 v25, v33, v23
	s_waitcnt lgkmcnt(0)
	v_add_f32_e32 v23, v23, v25
	ds_bpermute_b32 v25, v34, v23
	s_waitcnt lgkmcnt(0)
	v_add_f32_e32 v23, v23, v25
	ds_bpermute_b32 v25, v35, v23
	s_waitcnt lgkmcnt(0)
	v_add_f32_e32 v23, v23, v25
	v_fmamk_f32 v23, v23, 0x3a800000, v29
	v_mul_f32_e32 v25, 0x4b800000, v23
	v_cmp_gt_f32_e32 vcc, s15, v23
	s_nop 1
	v_cndmask_b32_e32 v23, v23, v25, vcc
	v_rsq_f32_e32 v23, v23
	s_nop 0
	v_mul_f32_e32 v25, 0x45800000, v23
	v_cndmask_b32_e32 v64, v23, v25, vcc
	v_pk_mul_f32 v[12:13], v[12:13], v[64:65] op_sel_hi:[1,0]
	v_pk_mul_f32 v[14:15], v[14:15], v[64:65] op_sel_hi:[1,0]
	v_pk_mul_f32 v[8:9], v[8:9], v[64:65] op_sel_hi:[1,0]
	v_pk_mul_f32 v[10:11], v[10:11], v[64:65] op_sel_hi:[1,0]
	v_mov_b32_e32 v25, v17
	v_pk_mul_f32 v[4:5], v[4:5], v[64:65] op_sel_hi:[1,0]
	v_pk_mul_f32 v[6:7], v[6:7], v[64:65] op_sel_hi:[1,0]
	v_cmp_lt_i32_e32 vcc, s7, v74
	s_or_b64 s[10:11], vcc, s[10:11]
	s_waitcnt vmcnt(4)
	v_pk_mul_f32 v[12:13], v[36:37], v[12:13]
	v_pk_mul_f32 v[14:15], v[38:39], v[14:15]
	v_pk_add_f32 v[36:37], v[44:45], 1.0 op_sel_hi:[1,0]
	v_pk_add_f32 v[38:39], v[46:47], 1.0 op_sel_hi:[1,0]
	v_pk_fma_f32 v[12:13], v[36:37], v[12:13], v[40:41]
	v_pk_fma_f32 v[14:15], v[38:39], v[14:15], v[42:43]
	v_cvt_pk_bf16_f32 v12, v12, v13
	v_cvt_pk_bf16_f32 v13, v14, v15
	global_store_dwordx2 v[20:21], v[12:13], off
	s_nop 0
	v_lshl_add_u64 v[44:45], v[66:67], 0, v[24:25]
	v_lshl_add_u64 v[66:67], v[66:67], 0, v[26:27]
	v_pk_mul_f32 v[8:9], v[140:141], v[8:9]
	v_pk_add_f32 v[12:13], v[164:165], 1.0 op_sel_hi:[1, 0]
	v_pk_mul_f32 v[10:11], v[142:143], v[10:11]
	v_pk_add_f32 v[14:15], v[166:167], 1.0 op_sel_hi:[1, 0]
	v_pk_fma_f32 v[8:9], v[12:13], v[8:9], v[152:153]
	v_pk_fma_f32 v[10:11], v[14:15], v[10:11], v[154:155]
	v_cvt_pk_bf16_f32 v8, v8, v9
	v_cvt_pk_bf16_f32 v9, v10, v11
	global_store_dwordx2 v[20:21], v[8:9], off offset:512
	s_nop 0
	v_pk_mul_f32 v[4:5], v[144:145], v[4:5]
	v_pk_add_f32 v[8:9], v[168:169], 1.0 op_sel_hi:[1, 0]
	v_pk_mul_f32 v[6:7], v[146:147], v[6:7]
	v_pk_add_f32 v[10:11], v[170:171], 1.0 op_sel_hi:[1, 0]
	v_pk_fma_f32 v[4:5], v[4:5], v[8:9], v[156:157]
	v_pk_fma_f32 v[6:7], v[6:7], v[10:11], v[158:159]
	v_cvt_pk_bf16_f32 v4, v4, v5
	v_cvt_pk_bf16_f32 v5, v6, v7
	global_store_dwordx2 v[20:21], v[4:5], off offset:1024
	v_pk_mul_f32 v[66:67], v[0:1], v[64:65] op_sel_hi:[1,0]
	v_pk_mul_f32 v[64:65], v[2:3], v[64:65] op_sel_hi:[1,0]
	s_waitcnt vmcnt(3)
	v_mov_b32_e32 v12, v48
	v_mov_b32_e32 v13, v49
	v_mov_b32_e32 v14, v50
	v_mov_b32_e32 v15, v51
	v_mov_b32_e32 v8, v52
	v_mov_b32_e32 v9, v53
	v_mov_b32_e32 v10, v54
	v_mov_b32_e32 v11, v55
	v_mov_b32_e32 v4, v56
	v_mov_b32_e32 v5, v57
	v_mov_b32_e32 v6, v58
	v_mov_b32_e32 v7, v59
	v_mov_b32_e32 v0, v60
	v_mov_b32_e32 v1, v61
	v_mov_b32_e32 v2, v62
	v_mov_b32_e32 v3, v63
	v_pk_mul_f32 v[36:37], v[66:67], v[148:149]
	v_pk_add_f32 v[40:41], v[172:173], 1.0 op_sel_hi:[1, 0]
	v_pk_mul_f32 v[38:39], v[64:65], v[150:151]
	v_pk_add_f32 v[42:43], v[174:175], 1.0 op_sel_hi:[1, 0]
	v_pk_fma_f32 v[36:37], v[36:37], v[40:41], v[160:161]
	v_pk_fma_f32 v[38:39], v[38:39], v[42:43], v[162:163]
	v_cvt_pk_bf16_f32 v36, v36, v37
	v_cvt_pk_bf16_f32 v37, v38, v39
	global_store_dwordx2 v[20:21], v[36:37], off offset:1536
	v_lshl_add_u64 v[20:21], v[20:21], 0, s[8:9]
	s_andn2_b64 exec, exec, s[10:11]
	s_cbranch_execnz .LBB0_663
